# P1 q/k epilogue: rope cos/sin pcol tables served from LDS (8KB copy at P1 start), ai=1 cr/sr loads hoisted, per-group vmcnt waits (which also waited on store acks) become lgkmcnt waits
# speedup vs baseline: 1.0096x; 1.0035x over previous
;     __host__ __device__ bool next(int i, Unit& u) const {
;         if (i >= R) return false;
;         const long L = (long)(rev ? R - 1 - i : i) * G + c; if (L >= nwg) return false;
;         int wgid = (int)L; { const int q = nwg / NXCD, r = nwg % NXCD, xcd = wgid % NXCD, off = wgid / NXCD; wgid = (xcd < r ? xcd * (q + 1) : r * (q + 1) + (xcd - r) * q) + off; }
;         const int nig = WGM * nN, gid = wgid / nig, fm = gid * WGM, gsz = (nM - fm) < WGM ? (nM - fm) : WGM;
;         u.pm = fm + ((wgid % nig) % gsz); u.pn = (wgid % nig) / gsz; u.idx = i; return true;
; template <class Epi, class Sched, bool ALIGN_EPI = false, bool SP2 = false>
; __device__ __forceinline__ void gemm_phase(PG8_LAS unsigned char* lds, const Gemm g, const Sched& S, const Epi& E) {
;     const int tid = threadIdx.x, wid = __builtin_amdgcn_readfirstlane(tid >> 6), lane = tid & 63, wr = wid >> 2, wc = wid & 3, fr = lane & 15, fq = lane >> 4;
;     const int K = g.K, nt = K / BK;
;     unsigned voffA[2], voffB[2];
; #pragma unroll
;     for (int i = 0; i < 2; ++i) { int R, C; stage_rc(tid * 16 + i * 8192, R, C); const int Rb = Epi::PERM ? ((R & ~31) + perm32(R & 31)) : R;
;         voffA[i] = (unsigned)(R * K + C) * 2u; voffB[i] = (unsigned)(Rb * K + C) * 2u; }
;     const size_t kstep = (size_t)(BK * 2);
;     const size_t hstep = (size_t)HALF * K * 2;
;     const size_t tstep = 2 * hstep;
;     const unsigned ldsw = (unsigned)wid * 1024u;
;     const int aoff = lds_byte(wr * 64 + fr, fq * 8), boff = lds_byte(wc * 32 + fr, fq * 8);
;     ...
;     Unit cur, nxt; int ui = 0;
;     if (!S.next(0, cur)) return;
;     f32x4 acc[2][2][4][2];
; #pragma unroll
;     for (int a = 0; a < 2; ++a)
; #pragma unroll
;         for (int b = 0; b < 2; ++b)
; #pragma unroll
;             for (int m = 0; m < 4; ++m)
; #pragma unroll
;                 for (int n = 0; n < 2; ++n) acc[a][b][m][n] = (f32x4){0.f, 0.f, 0.f, 0.f};
;     bf16x8 At[4][2], B0[2][2], B1[2][2];
;     const char* cA = (const char*)g.A + (size_t)cur.pm * tstep; const char* cB = (const char*)g.Bt + (size_t)cur.pn * tstep;
;     S.a_ready(cur);
;     if constexpr (SP2) {
;         PG8_STAGE(PG8_SB(0, 0), cB, voffB); PG8_STAGE(PG8_SB(0, 1), cB + hstep, voffB); PG8_STAGE(PG8_SA(0, 0), cA, voffA); PG8_STAGE(PG8_SA(0, 1), cA + hstep, voffA);
;         if (wr == 1) PG8_BAR;
;         PG8_WAIT_V(2); PG8_BAR;
.LBB0_234:
.LBB0_235:
	s_add_u32 s50, s62, 0x8000000
	s_addc_u32 s51, s63, 0
	s_add_u32 s58, s62, 0xf800000
	s_addc_u32 s59, s63, 0
	s_add_u32 s56, s62, 0xe000000
	s_addc_u32 s57, s63, 0
	s_cmp_lt_i32 s68, 2
	s_cselect_b64 s[4:5], -1, 0
	s_cmp_gt_u32 s33, 1
	s_cselect_b64 s[6:7], -1, 0
	s_and_b64 s[4:5], s[4:5], s[6:7]
	s_andn2_b64 vcc, exec, s[4:5]
	s_cbranch_vccnz .LBB0_335
	s_add_u32 s98, s62, 0x100000
	s_addc_u32 s99, s63, 0
	v_lshlrev_b32_e32 v252, 4, v208
	v_and_b32_e32 v253, 0x1000, v252
	v_add_u32_e32 v253, v253, v252
	s_nop 4
	global_load_dwordx4 v[248:251], v253, s[98:99]
	v_add_u32_e32 v252, 0x20800, v252
	s_waitcnt vmcnt(0)
	ds_write_b128 v252, v[248:251]
	s_waitcnt lgkmcnt(0)
	s_abs_i32 s0, s42
	v_cvt_f32_u32_e32 v2, s0
	s_add_i32 s1, s42, 0x3bf
	s_sub_i32 s4, 0xfffffc41, s42
	s_xor_b32 s5, s1, s42
	v_rcp_iflag_f32_e32 v2, v2
	s_max_i32 s1, s1, s4
	s_sub_i32 s4, 0, s0
	s_ashr_i32 s5, s5, 31
	v_mul_f32_e32 v2, 0x4f7ffffe, v2
	v_cvt_u32_f32_e32 v2, v2
	v_readfirstlane_b32 s9, v208
	v_readfirstlane_b32 s6, v2
	s_mul_i32 s4, s4, s6
	s_mul_hi_u32 s4, s6, s4
	s_add_i32 s6, s6, s4
	s_mul_hi_u32 s4, s1, s6
	s_mul_i32 s6, s4, s0
	s_sub_i32 s1, s1, s6
	s_add_i32 s7, s4, 1
	s_sub_i32 s6, s1, s0
	s_cmp_ge_u32 s1, s0
	s_cselect_b32 s4, s7, s4
	s_cselect_b32 s1, s6, s1
	s_add_i32 s6, s4, 1
	s_cmp_ge_u32 s1, s0
	s_cselect_b32 s0, s6, s4
	s_xor_b32 s0, s0, s5
	s_sub_i32 s36, s0, s5
	s_cmp_lt_i32 s36, 1
	s_cselect_b64 s[4:5], -1, 0
	s_cmpk_gt_i32 s2, 0x3bf
	s_cselect_b64 s[6:7], -1, 0
	s_or_b64 s[4:5], s[6:7], s[4:5]
	s_and_b64 vcc, exec, s[4:5]
	s_cbranch_vccnz .LBB0_267
	v_lshrrev_b32_e32 v2, 5, v208
	v_lshrrev_b32_e32 v4, 1, v208
	v_and_b32_e32 v2, 4, v2
	v_bfe_u32 v3, v208, 2, 2
	v_and_b32_e32 v4, 24, v4
	v_or3_b32 v2, v2, v3, v4
	v_lshlrev_b32_e32 v3, 4, v208
	s_waitcnt vmcnt(5)
	v_add_u32_e32 v10, 0x2000, v3
	v_lshrrev_b32_e32 v4, 7, v10
	s_movk_i32 s0, 0xe0
	v_and_b32_e32 v6, 32, v208
	v_and_or_b32 v5, v4, s0, v2
	s_waitcnt vmcnt(4)
	v_bitop3_b32 v11, v3, v6, 48 bitop3:0x6c
	v_and_b32_e32 v12, 64, v208
	v_bfe_u32 v13, v208, 2, 4
	s_movk_i32 s0, 0xf0
	v_or_b32_e32 v3, v11, v12
	v_and_or_b32 v4, v4, s0, v13
	v_lshl_or_b32 v140, v4, 11, v3
	v_lshrrev_b32_e32 v4, 3, v208
	s_movk_i32 s0, 0x60
	v_and_or_b32 v2, v4, s0, v2
	s_movk_i32 s0, 0x70
	s_ashr_i32 s39, s2, 31
	v_lshl_or_b32 v142, v2, 11, v3
	v_and_or_b32 v2, v4, s0, v13
	s_lshr_b32 s0, s39, 29
	s_add_i32 s0, s2, s0
	s_lshr_b32 s6, s9, 6
	s_ashr_i32 s1, s0, 3
	s_and_b32 s0, s0, -8
	s_lshr_b32 s37, s9, 8
	s_lshl_b32 s38, s6, 10
	s_sub_i32 s0, s2, s0
	s_cmp_lt_i32 s0, 0
	s_movk_i32 s40, 0x79
	s_cselect_b32 s4, s40, 0x78
	s_mul_i32 s0, s0, s4
	s_add_i32 s0, s0, s1
	s_mul_hi_i32 s1, s0, 0x66666667
	s_lshr_b32 s4, s1, 31
	s_ashr_i32 s1, s1, 4
	s_add_i32 s1, s1, s4
	s_lshl_b32 s4, s1, 3
	s_mul_i32 s1, s1, 40
	s_sub_i32 s0, s0, s1
	s_bfe_i32 s1, s0, 0x80000
	s_bfe_u32 s1, s1, 0x3000c
	s_add_i32 s1, s0, s1
	s_and_b32 s5, s1, 0xf8
	s_sub_i32 s0, s0, s5
	s_sext_i32_i8 s0, s0
	s_add_i32 s12, s4, s0
	s_bfe_i32 s0, s1, 0x80000
	s_sext_i32_i16 s0, s0
	s_lshr_b32 s8, s0, 3
	s_ashr_i32 s13, s12, 31
	s_bfe_i64 s[10:11], s[8:9], 0x100000
	s_lshl_b64 s[4:5], s[12:13], 19
	s_lshl_b64 s[10:11], s[10:11], 19
	s_add_u32 s30, s16, s10
	s_addc_u32 s31, s17, s11
	s_add_i32 s41, s38, 0x100
	s_add_i32 m0, s41, 0x10000
	v_lshl_or_b32 v138, v5, 11, v3
	global_load_lds_dwordx4 v142, s[30:31]
	s_add_i32 m0, s41, 0x12000
	s_add_u32 s10, s30, 0x40000
	global_load_lds_dwordx4 v138, s[30:31]
	s_addc_u32 s11, s31, 0
	s_add_i32 m0, s41, 0x14000
	v_lshl_or_b32 v144, v2, 11, v3
	global_load_lds_dwordx4 v142, s[10:11]
	s_add_i32 m0, s41, 0x16000
	s_add_u32 s28, s66, s4
	s_addc_u32 s29, s67, s5
	s_add_i32 s69, s41, 0x2000
	global_load_lds_dwordx4 v138, s[10:11]
	s_mov_b32 m0, s41
	s_add_u32 s4, s28, 0x40000
	global_load_lds_dwordx4 v144, s[28:29]
	s_mov_b32 m0, s69
	s_addc_u32 s5, s29, 0
	s_add_i32 s82, s41, 0x4000
	global_load_lds_dwordx4 v140, s[28:29]
	s_mov_b32 m0, s82
	s_add_i32 s83, s41, 0x6000
	global_load_lds_dwordx4 v144, s[4:5]
	s_mov_b32 m0, s83
	v_mov_b32_e32 v147, 0
	global_load_lds_dwordx4 v140, s[4:5]
	v_mov_b32_e32 v143, v147
	v_mov_b32_e32 v139, v147
	v_mov_b32_e32 v145, v147
	v_mov_b32_e32 v141, v147
	s_cmp_eq_u32 s37, 1
	s_mov_b32 s22, 0x10000
	v_lshl_add_u64 v[8:9], s[30:31], 0, v[142:143]
	v_lshl_add_u64 v[4:5], s[30:31], 0, v[138:139]
	s_mov_b32 s23, 0x14000
	v_lshl_add_u64 v[2:3], s[28:29], 0, v[144:145]
	s_cselect_b64 s[4:5], -1, 0
	s_cmp_lg_u32 s37, 1
	v_lshl_add_u64 v[6:7], s[28:29], 0, v[140:141]
	s_cbranch_scc1 .LBB0_239
	s_barrier

;     __device__ __forceinline__ void operator()(const f32x4 (&acc)[2][2][4][2], const Unit& u, int wr, int wc, int fr, int fq) const {
;     ...
;         const bool isK = (u.pn == 2);
;         const float* g = isK ? kg : qg; const float sc = isK ? 1.f : QK_C2;
;         bf16_t* base; int pitch;
;         if (isK) { base = KV + (size_t)row0 * 256 + wc * 64 + 8 * fq; pitch = 256; } else { base = MIX + (size_t)row0 * 1024 + (u.pn * 4 + wc) * 64 + 8 * fq; pitch = 1024; }
;         f32x4 gv[2][2];
; #pragma unroll
;         for (int bj = 0; bj < 2; ++bj)
; #pragma unroll
;             for (int n = 0; n < 2; ++n) gv[bj][n] = *(const f32x4*)(g + 32 * bj + 16 * n + 4 * fq) * sc;
;         const int rowt = u.pm * BM; const int t0 = rowt < ROWS_PROMPT ? (rowt & 4095) : ((rowt - ROWS_PROMPT) & 8191);
;         const int prow_base = (t0 >> 6) + wr;
; #pragma unroll
;         for (int ai = 0; ai < 2; ++ai) {
;             const int prow = prow_base + 2 * ai;
;             const f32x4 cr = *(const f32x4*)(cosT + prow * 16 + 4 * fq), sr = *(const f32x4*)(sinT + prow * 16 + 4 * fq);
; #pragma unroll
;             for (int m = 0; m < 4; ++m) {
;                 const int pcol = 16 * m + fr;
;                 const f32x4 cc = *(const f32x4*)(cosT + pcol * 16 + 4 * fq), sn = *(const f32x4*)(sinT + pcol * 16 + 4 * fq);
;                 float ss = 0.f;
; #pragma unroll
;                 for (int bj = 0; bj < 2; ++bj)
; #pragma unroll
;                     for (int n = 0; n < 2; ++n) { const f32x4 x = acc[ai][bj][m][n]; ss += (x[0] * x[0] + x[1] * x[1]) + (x[2] * x[2] + x[3] * x[3]); }
;                 ss += __shfl_xor(ss, 16); ss += __shfl_xor(ss, 32);
;                 const float rstd = __builtin_amdgcn_rsqf(ss * (1.0f / 64.0f) + RMS_EPS);
;                 bf16_t* rowp = base + (size_t)(ai * HALF + m * 16) * pitch;
; #pragma unroll
;                 for (int bj = 0; bj < 2; ++bj) { const f32x4 c = bj == 0 ? cr : cc, s = bj == 0 ? sr : sn;
;                     const f32x4 y0 = acc[ai][bj][m][0] * rstd * gv[bj][0], y1 = acc[ai][bj][m][1] * rstd * gv[bj][1];
;                     const f32x4 o0 = y0 * c - y1 * s, o1 = y1 * c + y0 * s;
;                     u32x4 w; w.x = cvt_pk_bf16(o0[0], o0[1]); w.y = cvt_pk_bf16(o0[2], o0[3]); w.z = cvt_pk_bf16(o1[0], o1[1]); w.w = cvt_pk_bf16(o1[2], o1[3]);
;                     *(u32x4*)(rowp + bj * 32) = w; }
.LBB0_255:
	s_and_b64 s[0:1], s[30:31], exec
	s_cselect_b32 s1, s55, s53
	s_cselect_b32 s0, s54, s52
	global_load_dwordx4 v[180:183], v199, s[0:1]
	global_load_dwordx4 v[184:187], v199, s[0:1] offset:64
	s_cmpk_lt_i32 s12, 0x80
	global_load_dwordx4 v[210:213], v199, s[0:1] offset:128
	global_load_dwordx4 v[214:217], v199, s[0:1] offset:192
	s_movk_i32 s0, 0xf00
	s_cselect_b32 s0, s0, 0x1f00
	s_and_b32 s0, s0, s19
	s_lshr_b32 s0, s0, 6
	s_add_i32 s0, s0, s37
	s_lshl_b32 s12, s0, 6
	v_lshl_add_u64 v[194:195], v[152:153], 0, s[12:13]
	v_lshl_add_u64 v[196:197], v[150:151], 0, s[12:13]
	global_load_dwordx4 v[130:133], v[194:195], off
	global_load_dwordx4 v[134:137], v[196:197], off
	global_load_dwordx4 v[240:243], v[194:195], off offset:128
	global_load_dwordx4 v[244:247], v[196:197], off offset:128
	global_load_dwordx4 v[218:221], v[154:155], off
	global_load_dwordx4 v[222:225], v[156:157], off
	v_pk_mul_f32 v[188:189], v[128:129], v[128:129]
	v_pk_mul_f32 v[190:191], v[126:127], v[126:127]
	v_pk_mul_f32 v[192:193], v[124:125], v[124:125]
	v_pk_mul_f32 v[226:227], v[122:123], v[122:123]
	v_pk_mov_b32 v[230:231], v[190:191], v[188:189] op_sel:[1,0]
	v_mov_b32_e32 v191, v189
	v_pk_mov_b32 v[188:189], v[226:227], v[192:193] op_sel:[1,0]
	v_mov_b32_e32 v227, v193
	v_mul_f32_e32 v146, v119, v119
	v_mul_f32_e32 v228, v121, v121
	v_pk_add_f32 v[190:191], v[230:231], v[190:191]
	v_pk_add_f32 v[188:189], v[188:189], v[226:227]
	v_and_b32_e32 v207, 64, v206
	v_mul_f32_e32 v209, v110, v110
	v_mul_f32_e32 v232, v111, v111
	v_mul_f32_e32 v233, v112, v112
	v_mul_f32_e32 v234, v113, v113
	v_pk_fma_f32 v[192:193], v[118:119], v[118:119], v[146:147] op_sel_hi:[1,1,0]
	v_pk_fma_f32 v[228:229], v[120:121], v[120:121], v[228:229] op_sel_hi:[1,1,0]
	v_pk_add_f32 v[190:191], v[190:191], v[190:191] op_sel:[0,1] op_sel_hi:[1,0]
	v_pk_add_f32 v[188:189], v[188:189], v[188:189] op_sel:[0,1] op_sel_hi:[1,0]
	v_xor_b32_e32 v177, 16, v206
	v_add_u32_e32 v207, 64, v207
	v_mov_b32_e32 v193, v233
	v_mov_b32_e32 v229, v234
	v_mov_b32_e32 v191, v209
	v_mov_b32_e32 v189, v232
	v_cmp_lt_i32_e32 vcc, v177, v207
	v_pk_add_f32 v[192:193], v[192:193], v[228:229]
	v_pk_add_f32 v[188:189], v[190:191], v[188:189]
	v_cndmask_b32_e32 v146, v206, v177, vcc
	v_pk_add_f32 v[188:189], v[188:189], v[192:193]
	v_lshlrev_b32_e32 v177, 2, v146
	v_add_f32_e32 v146, v188, v189
	ds_bpermute_b32 v188, v177, v146
	v_xor_b32_e32 v189, 32, v206
	v_cmp_lt_i32_e32 vcc, v189, v207
	v_mul_f32_e32 v209, v91, v91
	s_lshl_b32 s12, s28, 5
	v_cndmask_b32_e32 v189, v206, v189, vcc
	v_lshlrev_b32_e32 v207, 2, v189
	s_waitcnt lgkmcnt(0)
	v_add_f32_e32 v146, v146, v188
	ds_bpermute_b32 v188, v207, v146
	s_mul_i32 s0, s28, 0xa0
	s_mov_b32 s1, s13
	s_mov_b64 s[28:29], 0
	s_waitcnt lgkmcnt(0)
	v_add_f32_e32 v146, v146, v188
	v_fmamk_f32 v146, v146, 0x3c800000, v200
	v_rsq_f32_e32 v226, v146
	v_cndmask_b32_e64 v188, v205, 1.0, s[30:31]
	v_lshlrev_b32_e32 v146, 1, v148
	v_lshl_add_u64 v[228:229], v[178:179], 0, v[146:147]
	v_pk_mul_f32 v[234:235], v[122:123], v[226:227] op_sel_hi:[1,0]
	v_pk_mul_f32 v[236:237], v[124:125], v[226:227] op_sel_hi:[1,0]
	v_pk_mul_f32 v[230:231], v[128:129], v[226:227] op_sel_hi:[1,0]
	v_pk_mul_f32 v[232:233], v[126:127], v[226:227] op_sel_hi:[1,0]
	v_mul_f32_e32 v146, v90, v90
	s_waitcnt vmcnt(0)
	v_pk_mul_f32 v[178:179], v[188:189], v[182:183] op_sel_hi:[0,1]
	v_pk_mul_f32 v[182:183], v[188:189], v[186:187] op_sel_hi:[0,1]
	v_pk_mul_f32 v[184:185], v[188:189], v[184:185] op_sel_hi:[0,1]
	v_pk_mul_f32 v[190:191], v[188:189], v[180:181] op_sel_hi:[0,1]
	v_pk_mul_f32 v[180:181], v[188:189], v[212:213] op_sel_hi:[0,1]
	v_pk_mul_f32 v[192:193], v[188:189], v[210:211] op_sel_hi:[0,1]
	v_pk_mul_f32 v[186:187], v[188:189], v[216:217] op_sel_hi:[0,1]
	v_pk_mul_f32 v[188:189], v[188:189], v[214:215] op_sel_hi:[0,1]
	v_pk_mul_f32 v[214:215], v[182:183], v[236:237]
	v_pk_mul_f32 v[216:217], v[184:185], v[234:235]
	v_pk_mul_f32 v[210:211], v[190:191], v[232:233]
	v_pk_mul_f32 v[212:213], v[178:179], v[230:231]
	v_pk_mul_f32 v[230:231], v[130:131], v[216:217]
	v_pk_mul_f32 v[232:233], v[132:133], v[214:215]
	v_pk_mul_f32 v[216:217], v[134:135], v[216:217]
	v_pk_mul_f32 v[214:215], v[136:137], v[214:215]
	v_pk_fma_f32 v[232:233], v[136:137], v[212:213], v[232:233] neg_lo:[0,0,1] neg_hi:[0,0,1]
	v_pk_fma_f32 v[214:215], v[132:133], v[212:213], v[214:215]
	v_pk_fma_f32 v[212:213], v[130:131], v[210:211], v[216:217]
	v_pk_fma_f32 v[230:231], v[134:135], v[210:211], v[230:231] neg_lo:[0,0,1] neg_hi:[0,0,1]
	v_pk_mul_f32 v[216:217], v[112:113], v[226:227] op_sel_hi:[1,0]
	v_cvt_pk_bf16_f32 v210, v230, v231
	v_cvt_pk_bf16_f32 v211, v232, v233
	v_cvt_pk_bf16_f32 v212, v212, v213
	v_cvt_pk_bf16_f32 v213, v214, v215
	v_pk_mul_f32 v[214:215], v[110:111], v[226:227] op_sel_hi:[1,0]
	global_store_dwordx4 v[228:229], v[210:213], off
	v_pk_mul_f32 v[214:215], v[188:189], v[214:215]
	v_pk_mul_f32 v[216:217], v[186:187], v[216:217]
	v_pk_mul_f32 v[212:213], v[118:119], v[226:227] op_sel_hi:[1,0]
	v_pk_mul_f32 v[210:211], v[120:121], v[226:227] op_sel_hi:[1,0]
	v_pk_mul_f32 v[212:213], v[192:193], v[212:213]
	v_pk_mul_f32 v[226:227], v[222:223], v[214:215]
	v_pk_mul_f32 v[214:215], v[218:219], v[214:215]
	v_pk_mul_f32 v[210:211], v[180:181], v[210:211]
	v_pk_mul_f32 v[230:231], v[224:225], v[216:217]
	v_pk_fma_f32 v[226:227], v[218:219], v[212:213], v[226:227] neg_lo:[0,0,1] neg_hi:[0,0,1]
	v_pk_mul_f32 v[216:217], v[220:221], v[216:217]
	v_pk_fma_f32 v[212:213], v[222:223], v[212:213], v[214:215]
	v_pk_fma_f32 v[230:231], v[220:221], v[210:211], v[230:231] neg_lo:[0,0,1] neg_hi:[0,0,1]
; __device__ __forceinline__ unsigned cvt_pk_bf16(float lo, float hi) { unsigned r; asm volatile("v_cvt_pk_bf16_f32 %0, %1, %2" : "=v"(r) : "v"(lo), "v"(hi)); return r; }
;     __device__ __forceinline__ void operator()(const f32x4 (&acc)[2][2][4][2], const Unit& u, int wr, int wc, int fr, int fq) const {
;     ...
;                 const int pcol = 16 * m + fr;
;                 const f32x4 cc = *(const f32x4*)(cosT + pcol * 16 + 4 * fq), sn = *(const f32x4*)(sinT + pcol * 16 + 4 * fq);
;                 float ss = 0.f;
; #pragma unroll
;                 for (int bj = 0; bj < 2; ++bj)
; #pragma unroll
;                     for (int n = 0; n < 2; ++n) { const f32x4 x = acc[ai][bj][m][n]; ss += (x[0] * x[0] + x[1] * x[1]) + (x[2] * x[2] + x[3] * x[3]); }
;                 ss += __shfl_xor(ss, 16); ss += __shfl_xor(ss, 32);
;                 const float rstd = __builtin_amdgcn_rsqf(ss * (1.0f / 64.0f) + RMS_EPS);
;                 bf16_t* rowp = base + (size_t)(ai * HALF + m * 16) * pitch;
; #pragma unroll
;                 for (int bj = 0; bj < 2; ++bj) { const f32x4 c = bj == 0 ? cr : cc, s = bj == 0 ? sr : sn;
;                     const f32x4 y0 = acc[ai][bj][m][0] * rstd * gv[bj][0], y1 = acc[ai][bj][m][1] * rstd * gv[bj][1];
;                     const f32x4 o0 = y0 * c - y1 * s, o1 = y1 * c + y0 * s;
;                     u32x4 w; w.x = cvt_pk_bf16(o0[0], o0[1]); w.y = cvt_pk_bf16(o0[2], o0[3]); w.z = cvt_pk_bf16(o1[0], o1[1]); w.w = cvt_pk_bf16(o1[2], o1[3]);
;                     *(u32x4*)(rowp + bj * 32) = w; }
	v_pk_fma_f32 v[216:217], v[224:225], v[210:211], v[216:217]
	v_cvt_pk_bf16_f32 v210, v226, v227
	v_cvt_pk_bf16_f32 v211, v230, v231
	v_cvt_pk_bf16_f32 v212, v212, v213
	v_pk_mul_f32 v[218:219], v[116:117], v[116:117]
	v_cvt_pk_bf16_f32 v213, v216, v217
	global_store_dwordx4 v[228:229], v[210:213], off offset:64
	v_subrev_u32_e32 v252, s98, v160
	v_bfe_u32 v253, v252, 13, 1
	v_and_b32_e32 v252, 0xfff, v252
	v_lshl_or_b32 v252, v253, 12, v252
	v_add_u32_e32 v252, 0x20800, v252
	ds_read_b128 v[210:213], v252
	s_nop 0
	v_subrev_u32_e32 v252, s98, v158
	v_bfe_u32 v253, v252, 13, 1
	v_and_b32_e32 v252, 0xfff, v252
	v_lshl_or_b32 v252, v253, 12, v252
	v_add_u32_e32 v252, 0x20800, v252
	ds_read_b128 v[214:217], v252
	v_pk_mul_f32 v[220:221], v[114:115], v[114:115]
	s_nop 0
	v_pk_mov_b32 v[222:223], v[220:221], v[218:219] op_sel:[1,0]
	v_mov_b32_e32 v221, v219
	v_pk_add_f32 v[218:219], v[222:223], v[220:221]
	v_pk_mul_f32 v[220:221], v[108:109], v[108:109]
	v_pk_mul_f32 v[222:223], v[106:107], v[106:107]
	v_pk_add_f32 v[218:219], v[218:219], v[218:219] op_sel:[0,1] op_sel_hi:[1,0]
	v_pk_mov_b32 v[224:225], v[222:223], v[220:221] op_sel:[1,0]
	v_mov_b32_e32 v223, v221
	v_pk_add_f32 v[220:221], v[224:225], v[222:223]
	v_mov_b32_e32 v219, v146
	v_pk_add_f32 v[220:221], v[220:221], v[220:221] op_sel:[0,1] op_sel_hi:[1,0]
	v_mul_f32_e32 v146, v99, v99
	v_mov_b32_e32 v221, v209
	v_mul_f32_e32 v222, v92, v92
	v_pk_add_f32 v[218:219], v[218:219], v[220:221]
	v_pk_fma_f32 v[220:221], v[98:99], v[98:99], v[146:147] op_sel_hi:[1,1,0]
	v_mul_f32_e32 v146, v101, v101
	v_mul_f32_e32 v224, v93, v93
	v_mov_b32_e32 v221, v222
	v_pk_fma_f32 v[222:223], v[100:101], v[100:101], v[146:147] op_sel_hi:[1,1,0]
	s_nop 0
	v_mov_b32_e32 v223, v224
	v_pk_add_f32 v[220:221], v[220:221], v[222:223]
	v_lshl_add_u64 v[222:223], v[228:229], 0, s[12:13]
	v_pk_add_f32 v[218:219], v[218:219], v[220:221]
	s_nop 0
	v_add_f32_e32 v146, v218, v219
	ds_bpermute_b32 v209, v177, v146
	s_waitcnt lgkmcnt(0)
	v_add_f32_e32 v146, v146, v209
	ds_bpermute_b32 v209, v207, v146
	s_waitcnt lgkmcnt(0)
	v_add_f32_e32 v146, v146, v209
	v_fmamk_f32 v146, v146, 0x3c800000, v200
	v_rsq_f32_e32 v146, v146
	v_mul_f32_e32 v209, v75, v75
	v_pk_mul_f32 v[224:225], v[106:107], v[146:147] op_sel_hi:[1,0]
	v_pk_mul_f32 v[226:227], v[108:109], v[146:147] op_sel_hi:[1,0]
	v_pk_mul_f32 v[218:219], v[116:117], v[146:147] op_sel_hi:[1,0]
	v_pk_mul_f32 v[220:221], v[114:115], v[146:147] op_sel_hi:[1,0]
	v_pk_mul_f32 v[226:227], v[182:183], v[226:227]
	v_pk_mul_f32 v[224:225], v[184:185], v[224:225]
	v_pk_mul_f32 v[220:221], v[190:191], v[220:221]
	v_pk_mul_f32 v[218:219], v[178:179], v[218:219]
	v_pk_mul_f32 v[228:229], v[130:131], v[224:225]
	v_pk_mul_f32 v[230:231], v[132:133], v[226:227]
	v_pk_mul_f32 v[224:225], v[134:135], v[224:225]
	v_pk_mul_f32 v[226:227], v[136:137], v[226:227]
	v_pk_fma_f32 v[228:229], v[134:135], v[220:221], v[228:229] neg_lo:[0,0,1] neg_hi:[0,0,1]
	v_pk_fma_f32 v[226:227], v[132:133], v[218:219], v[226:227]
	v_pk_fma_f32 v[220:221], v[130:131], v[220:221], v[224:225]
	v_pk_fma_f32 v[230:231], v[136:137], v[218:219], v[230:231] neg_lo:[0,0,1] neg_hi:[0,0,1]
	v_cvt_pk_bf16_f32 v218, v228, v229
	v_pk_mul_f32 v[224:225], v[90:91], v[146:147] op_sel_hi:[1,0]
	v_cvt_pk_bf16_f32 v219, v230, v231
	v_cvt_pk_bf16_f32 v220, v220, v221
	v_cvt_pk_bf16_f32 v221, v226, v227
	v_pk_mul_f32 v[226:227], v[92:93], v[146:147] op_sel_hi:[1,0]
	global_store_dwordx4 v[222:223], v[218:221], off
	v_pk_mul_f32 v[226:227], v[186:187], v[226:227]
	v_pk_mul_f32 v[224:225], v[188:189], v[224:225]
	v_pk_mul_f32 v[218:219], v[100:101], v[146:147] op_sel_hi:[1,0]
	v_pk_mul_f32 v[220:221], v[98:99], v[146:147] op_sel_hi:[1,0]
	v_pk_mul_f32 v[218:219], v[180:181], v[218:219]
	v_pk_mul_f32 v[220:221], v[192:193], v[220:221]
	v_mul_f32_e32 v146, v74, v74
	s_waitcnt lgkmcnt(0)
	v_pk_mul_f32 v[228:229], v[210:211], v[224:225]
	v_pk_mul_f32 v[230:231], v[212:213], v[226:227]
	s_waitcnt lgkmcnt(0)
	v_pk_fma_f32 v[228:229], v[214:215], v[220:221], v[228:229] neg_lo:[0,0,1] neg_hi:[0,0,1]
	v_pk_fma_f32 v[230:231], v[216:217], v[218:219], v[230:231] neg_lo:[0,0,1] neg_hi:[0,0,1]
	v_pk_mul_f32 v[214:215], v[214:215], v[224:225]
	v_pk_mul_f32 v[216:217], v[216:217], v[226:227]
	s_nop 0
	v_pk_fma_f32 v[216:217], v[212:213], v[218:219], v[216:217]
	v_pk_fma_f32 v[212:213], v[210:211], v[220:221], v[214:215]
	v_cvt_pk_bf16_f32 v210, v228, v229
	v_cvt_pk_bf16_f32 v211, v230, v231
	v_pk_mul_f32 v[218:219], v[104:105], v[104:105]
	v_cvt_pk_bf16_f32 v212, v212, v213
	v_cvt_pk_bf16_f32 v213, v216, v217
	global_store_dwordx4 v[222:223], v[210:213], off offset:64
	v_subrev_u32_e32 v252, s98, v164
	v_bfe_u32 v253, v252, 13, 1
	v_and_b32_e32 v252, 0xfff, v252
	v_lshl_or_b32 v252, v253, 12, v252
	v_add_u32_e32 v252, 0x20800, v252
	ds_read_b128 v[210:213], v252
	s_nop 0
	v_subrev_u32_e32 v252, s98, v162
	v_bfe_u32 v253, v252, 13, 1
	v_and_b32_e32 v252, 0xfff, v252
	v_lshl_or_b32 v252, v253, 12, v252
	v_add_u32_e32 v252, 0x20800, v252
	ds_read_b128 v[214:217], v252
	v_pk_mul_f32 v[220:221], v[102:103], v[102:103]
	v_lshl_add_u64 v[222:223], v[222:223], 0, s[12:13]
	v_pk_mov_b32 v[224:225], v[220:221], v[218:219] op_sel:[1,0]
	v_mov_b32_e32 v221, v219
	v_pk_add_f32 v[218:219], v[224:225], v[220:221]
	v_pk_mul_f32 v[220:221], v[96:97], v[96:97]
	v_pk_mul_f32 v[224:225], v[94:95], v[94:95]
	v_pk_add_f32 v[218:219], v[218:219], v[218:219] op_sel:[0,1] op_sel_hi:[1,0]
	v_pk_mov_b32 v[226:227], v[224:225], v[220:221] op_sel:[1,0]
	v_mov_b32_e32 v225, v221
	v_pk_add_f32 v[220:221], v[226:227], v[224:225]
	v_mov_b32_e32 v219, v146
	v_pk_add_f32 v[220:221], v[220:221], v[220:221] op_sel:[0,1] op_sel_hi:[1,0]
	v_mul_f32_e32 v146, v83, v83
	v_mov_b32_e32 v221, v209
	v_mul_f32_e32 v224, v76, v76
	v_pk_add_f32 v[218:219], v[218:219], v[220:221]
	v_pk_fma_f32 v[220:221], v[82:83], v[82:83], v[146:147] op_sel_hi:[1,1,0]
	v_mul_f32_e32 v146, v85, v85
	v_mul_f32_e32 v226, v77, v77
	v_mov_b32_e32 v221, v224
	v_pk_fma_f32 v[224:225], v[84:85], v[84:85], v[146:147] op_sel_hi:[1,1,0]
	s_nop 0
	v_mov_b32_e32 v225, v226
	v_pk_add_f32 v[220:221], v[220:221], v[224:225]
	s_nop 0
	v_pk_add_f32 v[218:219], v[218:219], v[220:221]
	s_nop 0
	v_add_f32_e32 v146, v218, v219
	ds_bpermute_b32 v209, v177, v146
	s_waitcnt lgkmcnt(0)
; __device__ __forceinline__ unsigned cvt_pk_bf16(float lo, float hi) { unsigned r; asm volatile("v_cvt_pk_bf16_f32 %0, %1, %2" : "=v"(r) : "v"(lo), "v"(hi)); return r; }
;     __device__ __forceinline__ void operator()(const f32x4 (&acc)[2][2][4][2], const Unit& u, int wr, int wc, int fr, int fq) const {
;     ...
;             for (int m = 0; m < 4; ++m) {
;                 const int pcol = 16 * m + fr;
;                 const f32x4 cc = *(const f32x4*)(cosT + pcol * 16 + 4 * fq), sn = *(const f32x4*)(sinT + pcol * 16 + 4 * fq);
;                 float ss = 0.f;
; #pragma unroll
;                 for (int bj = 0; bj < 2; ++bj)
; #pragma unroll
;                     for (int n = 0; n < 2; ++n) { const f32x4 x = acc[ai][bj][m][n]; ss += (x[0] * x[0] + x[1] * x[1]) + (x[2] * x[2] + x[3] * x[3]); }
;                 ss += __shfl_xor(ss, 16); ss += __shfl_xor(ss, 32);
;                 const float rstd = __builtin_amdgcn_rsqf(ss * (1.0f / 64.0f) + RMS_EPS);
;                 bf16_t* rowp = base + (size_t)(ai * HALF + m * 16) * pitch;
; #pragma unroll
;                 for (int bj = 0; bj < 2; ++bj) { const f32x4 c = bj == 0 ? cr : cc, s = bj == 0 ? sr : sn;
;                     const f32x4 y0 = acc[ai][bj][m][0] * rstd * gv[bj][0], y1 = acc[ai][bj][m][1] * rstd * gv[bj][1];
;                     const f32x4 o0 = y0 * c - y1 * s, o1 = y1 * c + y0 * s;
;                     u32x4 w; w.x = cvt_pk_bf16(o0[0], o0[1]); w.y = cvt_pk_bf16(o0[2], o0[3]); w.z = cvt_pk_bf16(o1[0], o1[1]); w.w = cvt_pk_bf16(o1[2], o1[3]);
;                     *(u32x4*)(rowp + bj * 32) = w; }
	v_add_f32_e32 v146, v146, v209
	ds_bpermute_b32 v209, v207, v146
	s_waitcnt lgkmcnt(0)
	v_add_f32_e32 v146, v146, v209
	v_fmamk_f32 v146, v146, 0x3c800000, v200
	v_rsq_f32_e32 v146, v146
	v_mul_f32_e32 v209, v67, v67
	v_pk_mul_f32 v[224:225], v[94:95], v[146:147] op_sel_hi:[1,0]
	v_pk_mul_f32 v[226:227], v[96:97], v[146:147] op_sel_hi:[1,0]
	v_pk_mul_f32 v[218:219], v[104:105], v[146:147] op_sel_hi:[1,0]
	v_pk_mul_f32 v[220:221], v[102:103], v[146:147] op_sel_hi:[1,0]
	v_pk_mul_f32 v[226:227], v[182:183], v[226:227]
	v_pk_mul_f32 v[224:225], v[184:185], v[224:225]
	v_pk_mul_f32 v[220:221], v[190:191], v[220:221]
	v_pk_mul_f32 v[218:219], v[178:179], v[218:219]
	v_pk_mul_f32 v[228:229], v[130:131], v[224:225]
	v_pk_mul_f32 v[230:231], v[132:133], v[226:227]
	v_pk_mul_f32 v[224:225], v[134:135], v[224:225]
	v_pk_mul_f32 v[226:227], v[136:137], v[226:227]
	v_pk_fma_f32 v[228:229], v[134:135], v[220:221], v[228:229] neg_lo:[0,0,1] neg_hi:[0,0,1]
	v_pk_fma_f32 v[226:227], v[132:133], v[218:219], v[226:227]
	v_pk_fma_f32 v[220:221], v[130:131], v[220:221], v[224:225]
	v_pk_fma_f32 v[230:231], v[136:137], v[218:219], v[230:231] neg_lo:[0,0,1] neg_hi:[0,0,1]
	v_cvt_pk_bf16_f32 v218, v228, v229
	v_pk_mul_f32 v[224:225], v[74:75], v[146:147] op_sel_hi:[1,0]
	v_cvt_pk_bf16_f32 v219, v230, v231
	v_cvt_pk_bf16_f32 v220, v220, v221
	v_cvt_pk_bf16_f32 v221, v226, v227
	v_pk_mul_f32 v[226:227], v[76:77], v[146:147] op_sel_hi:[1,0]
	global_store_dwordx4 v[222:223], v[218:221], off
	v_pk_mul_f32 v[226:227], v[186:187], v[226:227]
	v_pk_mul_f32 v[224:225], v[188:189], v[224:225]
	v_pk_mul_f32 v[218:219], v[84:85], v[146:147] op_sel_hi:[1,0]
	v_pk_mul_f32 v[220:221], v[82:83], v[146:147] op_sel_hi:[1,0]
	v_pk_mul_f32 v[218:219], v[180:181], v[218:219]
	v_pk_mul_f32 v[220:221], v[192:193], v[220:221]
	v_mul_f32_e32 v146, v66, v66
	s_waitcnt lgkmcnt(0)
	v_pk_mul_f32 v[228:229], v[210:211], v[224:225]
	v_pk_mul_f32 v[230:231], v[212:213], v[226:227]
	s_waitcnt lgkmcnt(0)
	v_pk_fma_f32 v[228:229], v[214:215], v[220:221], v[228:229] neg_lo:[0,0,1] neg_hi:[0,0,1]
	v_pk_fma_f32 v[230:231], v[216:217], v[218:219], v[230:231] neg_lo:[0,0,1] neg_hi:[0,0,1]
	v_pk_mul_f32 v[214:215], v[214:215], v[224:225]
	v_pk_mul_f32 v[216:217], v[216:217], v[226:227]
	s_nop 0
	v_pk_fma_f32 v[216:217], v[212:213], v[218:219], v[216:217]
	v_pk_fma_f32 v[212:213], v[210:211], v[220:221], v[214:215]
	v_cvt_pk_bf16_f32 v210, v228, v229
	v_cvt_pk_bf16_f32 v211, v230, v231
	v_pk_mul_f32 v[218:219], v[88:89], v[88:89]
	v_cvt_pk_bf16_f32 v212, v212, v213
	v_cvt_pk_bf16_f32 v213, v216, v217
	global_store_dwordx4 v[222:223], v[210:213], off offset:64
	v_subrev_u32_e32 v252, s98, v168
	v_bfe_u32 v253, v252, 13, 1
	v_and_b32_e32 v252, 0xfff, v252
	v_lshl_or_b32 v252, v253, 12, v252
	v_add_u32_e32 v252, 0x20800, v252
	ds_read_b128 v[210:213], v252
	s_nop 0
	v_subrev_u32_e32 v252, s98, v166
	v_bfe_u32 v253, v252, 13, 1
	v_and_b32_e32 v252, 0xfff, v252
	v_lshl_or_b32 v252, v253, 12, v252
	v_add_u32_e32 v252, 0x20800, v252
	ds_read_b128 v[214:217], v252
	v_pk_mul_f32 v[220:221], v[86:87], v[86:87]
	s_nop 0
	v_pk_mov_b32 v[224:225], v[220:221], v[218:219] op_sel:[1,0]
	v_mov_b32_e32 v221, v219
	v_pk_add_f32 v[218:219], v[224:225], v[220:221]
	v_pk_mul_f32 v[220:221], v[80:81], v[80:81]
	v_pk_mul_f32 v[224:225], v[78:79], v[78:79]
	v_pk_add_f32 v[218:219], v[218:219], v[218:219] op_sel:[0,1] op_sel_hi:[1,0]
	v_pk_mov_b32 v[226:227], v[224:225], v[220:221] op_sel:[1,0]
	v_mov_b32_e32 v225, v221
	v_pk_add_f32 v[220:221], v[226:227], v[224:225]
	v_mov_b32_e32 v219, v146
	v_pk_add_f32 v[220:221], v[220:221], v[220:221] op_sel:[0,1] op_sel_hi:[1,0]
	v_mul_f32_e32 v146, v71, v71
	v_mov_b32_e32 v221, v209
	v_mul_f32_e32 v224, v68, v68
	v_pk_add_f32 v[218:219], v[218:219], v[220:221]
	v_pk_fma_f32 v[220:221], v[70:71], v[70:71], v[146:147] op_sel_hi:[1,1,0]
	v_mul_f32_e32 v146, v73, v73
	v_mul_f32_e32 v226, v69, v69
	v_mov_b32_e32 v221, v224
	v_pk_fma_f32 v[224:225], v[72:73], v[72:73], v[146:147] op_sel_hi:[1,1,0]
	s_nop 0
	v_mov_b32_e32 v225, v226
	v_pk_add_f32 v[220:221], v[220:221], v[224:225]
	s_nop 0
	v_pk_add_f32 v[218:219], v[218:219], v[220:221]
	s_nop 0
	v_add_f32_e32 v146, v218, v219
	ds_bpermute_b32 v209, v177, v146
	v_lshl_add_u64 v[218:219], v[222:223], 0, s[12:13]
	s_waitcnt lgkmcnt(0)
	v_add_f32_e32 v146, v146, v209
	ds_bpermute_b32 v209, v207, v146
	s_waitcnt lgkmcnt(0)
	v_add_f32_e32 v146, v146, v209
	v_fmamk_f32 v146, v146, 0x3c800000, v200
	v_rsq_f32_e32 v146, v146
	v_mul_f32_e32 v209, v42, v42
	v_pk_mul_f32 v[224:225], v[78:79], v[146:147] op_sel_hi:[1,0]
	v_pk_mul_f32 v[226:227], v[80:81], v[146:147] op_sel_hi:[1,0]
	v_pk_mul_f32 v[220:221], v[88:89], v[146:147] op_sel_hi:[1,0]
	v_pk_mul_f32 v[222:223], v[86:87], v[146:147] op_sel_hi:[1,0]
	v_pk_mul_f32 v[226:227], v[182:183], v[226:227]
	v_pk_mul_f32 v[224:225], v[184:185], v[224:225]
	v_pk_mul_f32 v[222:223], v[190:191], v[222:223]
	v_pk_mul_f32 v[220:221], v[178:179], v[220:221]
	v_pk_mul_f32 v[236:237], v[130:131], v[224:225]
	v_pk_mul_f32 v[238:239], v[132:133], v[226:227]
	v_pk_mul_f32 v[224:225], v[134:135], v[224:225]
	v_pk_mul_f32 v[226:227], v[136:137], v[226:227]
	v_pk_mul_f32 v[232:233], v[66:67], v[146:147] op_sel_hi:[1,0]
	v_pk_mul_f32 v[234:235], v[68:69], v[146:147] op_sel_hi:[1,0]
	v_pk_fma_f32 v[136:137], v[136:137], v[220:221], v[238:239] neg_lo:[0,0,1] neg_hi:[0,0,1]
	v_pk_fma_f32 v[220:221], v[132:133], v[220:221], v[226:227]
	v_pk_fma_f32 v[132:133], v[130:131], v[222:223], v[224:225]
	v_pk_mul_f32 v[228:229], v[72:73], v[146:147] op_sel_hi:[1,0]
	v_pk_mul_f32 v[230:231], v[70:71], v[146:147] op_sel_hi:[1,0]
	v_pk_mul_f32 v[234:235], v[186:187], v[234:235]
	v_pk_mul_f32 v[232:233], v[188:189], v[232:233]
	v_pk_fma_f32 v[134:135], v[134:135], v[222:223], v[236:237] neg_lo:[0,0,1] neg_hi:[0,0,1]
	v_pk_mul_f32 v[230:231], v[192:193], v[230:231]
	v_cvt_pk_bf16_f32 v130, v134, v135
	v_cvt_pk_bf16_f32 v131, v136, v137
	v_cvt_pk_bf16_f32 v132, v132, v133
	v_cvt_pk_bf16_f32 v133, v220, v221
	v_pk_mul_f32 v[228:229], v[180:181], v[228:229]
	global_store_dwordx4 v[218:219], v[130:133], off
	v_pk_mul_f32 v[220:221], v[60:61], v[60:61]
	v_pk_mul_f32 v[222:223], v[58:59], v[58:59]
	v_mul_f32_e32 v146, v51, v51
	s_waitcnt lgkmcnt(0)
; __device__ __forceinline__ unsigned cvt_pk_bf16(float lo, float hi) { unsigned r; asm volatile("v_cvt_pk_bf16_f32 %0, %1, %2" : "=v"(r) : "v"(lo), "v"(hi)); return r; }
;     __device__ __forceinline__ void operator()(const f32x4 (&acc)[2][2][4][2], const Unit& u, int wr, int wc, int fr, int fq) const {
;     ...
; #pragma unroll
;         for (int ai = 0; ai < 2; ++ai) {
;             const int prow = prow_base + 2 * ai;
;             const f32x4 cr = *(const f32x4*)(cosT + prow * 16 + 4 * fq), sr = *(const f32x4*)(sinT + prow * 16 + 4 * fq);
; #pragma unroll
;             for (int m = 0; m < 4; ++m) {
;                 const int pcol = 16 * m + fr;
;                 const f32x4 cc = *(const f32x4*)(cosT + pcol * 16 + 4 * fq), sn = *(const f32x4*)(sinT + pcol * 16 + 4 * fq);
;                 float ss = 0.f;
; #pragma unroll
;                 for (int bj = 0; bj < 2; ++bj)
; #pragma unroll
;                     for (int n = 0; n < 2; ++n) { const f32x4 x = acc[ai][bj][m][n]; ss += (x[0] * x[0] + x[1] * x[1]) + (x[2] * x[2] + x[3] * x[3]); }
;                 ss += __shfl_xor(ss, 16); ss += __shfl_xor(ss, 32);
;                 const float rstd = __builtin_amdgcn_rsqf(ss * (1.0f / 64.0f) + RMS_EPS);
;                 bf16_t* rowp = base + (size_t)(ai * HALF + m * 16) * pitch;
; #pragma unroll
;                 for (int bj = 0; bj < 2; ++bj) { const f32x4 c = bj == 0 ? cr : cc, s = bj == 0 ? sr : sn;
;                     const f32x4 y0 = acc[ai][bj][m][0] * rstd * gv[bj][0], y1 = acc[ai][bj][m][1] * rstd * gv[bj][1];
;                     const f32x4 o0 = y0 * c - y1 * s, o1 = y1 * c + y0 * s;
;                     u32x4 w; w.x = cvt_pk_bf16(o0[0], o0[1]); w.y = cvt_pk_bf16(o0[2], o0[3]); w.z = cvt_pk_bf16(o1[0], o1[1]); w.w = cvt_pk_bf16(o1[2], o1[3]);
;                     *(u32x4*)(rowp + bj * 32) = w; }
	v_pk_mul_f32 v[130:131], v[210:211], v[232:233]
	v_pk_mul_f32 v[132:133], v[212:213], v[234:235]
	s_waitcnt lgkmcnt(0)
	v_pk_fma_f32 v[130:131], v[214:215], v[230:231], v[130:131] neg_lo:[0,0,1] neg_hi:[0,0,1]
	v_pk_fma_f32 v[132:133], v[216:217], v[228:229], v[132:133] neg_lo:[0,0,1] neg_hi:[0,0,1]
	v_pk_mul_f32 v[134:135], v[214:215], v[232:233]
	v_pk_mul_f32 v[136:137], v[216:217], v[234:235]
	v_pk_fma_f32 v[134:135], v[210:211], v[230:231], v[134:135]
	v_pk_fma_f32 v[136:137], v[212:213], v[228:229], v[136:137]
	v_cvt_pk_bf16_f32 v130, v130, v131
	v_cvt_pk_bf16_f32 v131, v132, v133
	v_cvt_pk_bf16_f32 v132, v134, v135
	v_pk_mul_f32 v[214:215], v[64:65], v[64:65]
	v_cvt_pk_bf16_f32 v133, v136, v137
	global_store_dwordx4 v[218:219], v[130:133], off offset:64
	s_nop 1
	v_mov_b64 v[130:131], v[240:241]
	v_mov_b64 v[132:133], v[242:243]
	s_nop 0
	s_nop 1
	v_mov_b64 v[134:135], v[244:245]
	v_mov_b64 v[136:137], v[246:247]
	s_nop 0
	v_subrev_u32_e32 v252, s98, v156
	v_bfe_u32 v253, v252, 13, 1
	v_and_b32_e32 v252, 0xfff, v252
	v_lshl_or_b32 v252, v253, 12, v252
	v_add_u32_e32 v252, 0x20800, v252
	ds_read_b128 v[194:197], v252
	v_subrev_u32_e32 v252, s98, v154
	v_bfe_u32 v253, v252, 13, 1
	v_and_b32_e32 v252, 0xfff, v252
	v_lshl_or_b32 v252, v253, 12, v252
	v_add_u32_e32 v252, 0x20800, v252
	ds_read_b128 v[210:213], v252
	v_pk_mul_f32 v[216:217], v[62:63], v[62:63]
	v_mul_f32_e32 v224, v53, v53
	v_pk_mov_b32 v[226:227], v[216:217], v[214:215] op_sel:[1,0]
	v_mov_b32_e32 v217, v215
	v_pk_mov_b32 v[214:215], v[222:223], v[220:221] op_sel:[1,0]
	v_mov_b32_e32 v223, v221
	v_pk_add_f32 v[216:217], v[226:227], v[216:217]
	v_pk_add_f32 v[214:215], v[214:215], v[222:223]
	v_mul_f32_e32 v228, v43, v43
	v_mul_f32_e32 v229, v44, v44
	v_mul_f32_e32 v230, v45, v45
	v_pk_fma_f32 v[220:221], v[50:51], v[50:51], v[146:147] op_sel_hi:[1,1,0]
	v_pk_fma_f32 v[224:225], v[52:53], v[52:53], v[224:225] op_sel_hi:[1,1,0]
	v_pk_add_f32 v[216:217], v[216:217], v[216:217] op_sel:[0,1] op_sel_hi:[1,0]
	v_pk_add_f32 v[214:215], v[214:215], v[214:215] op_sel:[0,1] op_sel_hi:[1,0]
	v_mov_b32_e32 v221, v229
	v_mov_b32_e32 v225, v230
	v_mov_b32_e32 v217, v209
	v_mov_b32_e32 v215, v228
	v_pk_add_f32 v[220:221], v[220:221], v[224:225]
	v_pk_add_f32 v[214:215], v[216:217], v[214:215]
	v_lshl_add_u64 v[218:219], v[218:219], 0, s[0:1]
	v_pk_add_f32 v[214:215], v[214:215], v[220:221]
	s_nop 0
	v_add_f32_e32 v146, v214, v215
	ds_bpermute_b32 v209, v177, v146
	s_waitcnt lgkmcnt(0)
	v_add_f32_e32 v146, v146, v209
	ds_bpermute_b32 v209, v207, v146
	s_waitcnt lgkmcnt(0)
	v_add_f32_e32 v146, v146, v209
	v_fmamk_f32 v146, v146, 0x3c800000, v200
	v_rsq_f32_e32 v146, v146
	v_mul_f32_e32 v209, v27, v27
	v_pk_mul_f32 v[220:221], v[58:59], v[146:147] op_sel_hi:[1,0]
	v_pk_mul_f32 v[230:231], v[44:45], v[146:147] op_sel_hi:[1,0]
	v_pk_mul_f32 v[216:217], v[62:63], v[146:147] op_sel_hi:[1,0]
	v_pk_mul_f32 v[224:225], v[52:53], v[146:147] op_sel_hi:[1,0]
	v_pk_mul_f32 v[228:229], v[42:43], v[146:147] op_sel_hi:[1,0]
	v_pk_mul_f32 v[220:221], v[184:185], v[220:221]
	v_pk_mul_f32 v[230:231], v[186:187], v[230:231]
	v_pk_mul_f32 v[222:223], v[60:61], v[146:147] op_sel_hi:[1,0]
	v_pk_mul_f32 v[226:227], v[50:51], v[146:147] op_sel_hi:[1,0]
	v_pk_mul_f32 v[216:217], v[190:191], v[216:217]
	v_pk_mul_f32 v[224:225], v[180:181], v[224:225]
	v_pk_mul_f32 v[228:229], v[188:189], v[228:229]
	v_pk_mul_f32 v[214:215], v[64:65], v[146:147] op_sel_hi:[1,0]
	v_pk_mul_f32 v[222:223], v[182:183], v[222:223]
	v_pk_mul_f32 v[226:227], v[192:193], v[226:227]
	v_pk_mul_f32 v[214:215], v[178:179], v[214:215]
	v_mul_f32_e32 v146, v26, v26
	s_waitcnt lgkmcnt(0)
	v_pk_mul_f32 v[232:233], v[130:131], v[220:221]
	s_waitcnt lgkmcnt(0)
	v_pk_mul_f32 v[220:221], v[134:135], v[220:221]
	s_waitcnt lgkmcnt(0)
	v_pk_mul_f32 v[238:239], v[196:197], v[230:231]
	v_pk_mul_f32 v[236:237], v[194:195], v[228:229]
	s_waitcnt lgkmcnt(0)
	v_pk_mul_f32 v[228:229], v[210:211], v[228:229]
	v_pk_fma_f32 v[232:233], v[134:135], v[216:217], v[232:233] neg_lo:[0,0,1] neg_hi:[0,0,1]
	v_pk_fma_f32 v[216:217], v[130:131], v[216:217], v[220:221]
	v_pk_fma_f32 v[220:221], v[212:213], v[224:225], v[238:239] neg_lo:[0,0,1] neg_hi:[0,0,1]
	v_pk_mul_f32 v[212:213], v[212:213], v[230:231]
	v_pk_mul_f32 v[234:235], v[132:133], v[222:223]
	v_pk_mul_f32 v[222:223], v[136:137], v[222:223]
	v_pk_fma_f32 v[212:213], v[196:197], v[224:225], v[212:213]
	v_pk_fma_f32 v[196:197], v[194:195], v[226:227], v[228:229]
	v_pk_fma_f32 v[234:235], v[136:137], v[214:215], v[234:235] neg_lo:[0,0,1] neg_hi:[0,0,1]
	v_pk_fma_f32 v[222:223], v[132:133], v[214:215], v[222:223]
	v_pk_fma_f32 v[210:211], v[210:211], v[226:227], v[236:237] neg_lo:[0,0,1] neg_hi:[0,0,1]
	v_cvt_pk_bf16_f32 v214, v232, v233
	v_cvt_pk_bf16_f32 v215, v234, v235
	v_cvt_pk_bf16_f32 v216, v216, v217
	v_cvt_pk_bf16_f32 v217, v222, v223
	global_store_dwordx4 v[218:219], v[214:217], off
	v_cvt_pk_bf16_f32 v194, v210, v211
	v_cvt_pk_bf16_f32 v195, v220, v221
	v_cvt_pk_bf16_f32 v196, v196, v197
	v_cvt_pk_bf16_f32 v197, v212, v213
	global_store_dwordx4 v[218:219], v[194:197], off offset:64
	v_subrev_u32_e32 v252, s98, v160
	v_bfe_u32 v253, v252, 13, 1
	v_and_b32_e32 v252, 0xfff, v252
	v_lshl_or_b32 v252, v253, 12, v252
	v_add_u32_e32 v252, 0x20800, v252
	ds_read_b128 v[194:197], v252
	s_nop 0
	v_subrev_u32_e32 v252, s98, v158
	v_bfe_u32 v253, v252, 13, 1
	v_and_b32_e32 v252, 0xfff, v252
	v_lshl_or_b32 v252, v253, 12, v252
	v_add_u32_e32 v252, 0x20800, v252
	ds_read_b128 v[210:213], v252
	v_pk_mul_f32 v[214:215], v[56:57], v[56:57]
	v_pk_mul_f32 v[216:217], v[54:55], v[54:55]
	v_lshl_add_u64 v[218:219], v[218:219], 0, s[12:13]
	v_pk_mov_b32 v[220:221], v[216:217], v[214:215] op_sel:[1,0]
	v_mov_b32_e32 v217, v215
	v_pk_add_f32 v[214:215], v[220:221], v[216:217]
	v_pk_mul_f32 v[216:217], v[48:49], v[48:49]
	v_pk_mul_f32 v[220:221], v[46:47], v[46:47]
	v_pk_add_f32 v[214:215], v[214:215], v[214:215] op_sel:[0,1] op_sel_hi:[1,0]
	v_pk_mov_b32 v[222:223], v[220:221], v[216:217] op_sel:[1,0]
	v_mov_b32_e32 v221, v217
	v_pk_add_f32 v[216:217], v[222:223], v[220:221]
	v_mov_b32_e32 v215, v146
	v_pk_add_f32 v[216:217], v[216:217], v[216:217] op_sel:[0,1] op_sel_hi:[1,0]
	v_mul_f32_e32 v146, v35, v35
	v_mov_b32_e32 v217, v209
	v_mul_f32_e32 v220, v28, v28
	v_pk_add_f32 v[214:215], v[214:215], v[216:217]
	v_pk_fma_f32 v[216:217], v[34:35], v[34:35], v[146:147] op_sel_hi:[1,1,0]
	v_mul_f32_e32 v146, v37, v37
	v_mul_f32_e32 v222, v29, v29
	v_mov_b32_e32 v217, v220
	v_pk_fma_f32 v[220:221], v[36:37], v[36:37], v[146:147] op_sel_hi:[1,1,0]
	s_nop 0
	v_mov_b32_e32 v221, v222
	v_pk_add_f32 v[216:217], v[216:217], v[220:221]
	s_nop 0
	v_pk_add_f32 v[214:215], v[214:215], v[216:217]
	s_nop 0
	v_add_f32_e32 v146, v214, v215
	ds_bpermute_b32 v209, v177, v146
	s_waitcnt lgkmcnt(0)
; __device__ __forceinline__ unsigned cvt_pk_bf16(float lo, float hi) { unsigned r; asm volatile("v_cvt_pk_bf16_f32 %0, %1, %2" : "=v"(r) : "v"(lo), "v"(hi)); return r; }
;     __device__ __forceinline__ void operator()(const f32x4 (&acc)[2][2][4][2], const Unit& u, int wr, int wc, int fr, int fq) const {
;     ...
;             for (int m = 0; m < 4; ++m) {
;                 const int pcol = 16 * m + fr;
;                 const f32x4 cc = *(const f32x4*)(cosT + pcol * 16 + 4 * fq), sn = *(const f32x4*)(sinT + pcol * 16 + 4 * fq);
;                 float ss = 0.f;
; #pragma unroll
;                 for (int bj = 0; bj < 2; ++bj)
; #pragma unroll
;                     for (int n = 0; n < 2; ++n) { const f32x4 x = acc[ai][bj][m][n]; ss += (x[0] * x[0] + x[1] * x[1]) + (x[2] * x[2] + x[3] * x[3]); }
;                 ss += __shfl_xor(ss, 16); ss += __shfl_xor(ss, 32);
;                 const float rstd = __builtin_amdgcn_rsqf(ss * (1.0f / 64.0f) + RMS_EPS);
;                 bf16_t* rowp = base + (size_t)(ai * HALF + m * 16) * pitch;
; #pragma unroll
;                 for (int bj = 0; bj < 2; ++bj) { const f32x4 c = bj == 0 ? cr : cc, s = bj == 0 ? sr : sn;
;                     const f32x4 y0 = acc[ai][bj][m][0] * rstd * gv[bj][0], y1 = acc[ai][bj][m][1] * rstd * gv[bj][1];
;                     const f32x4 o0 = y0 * c - y1 * s, o1 = y1 * c + y0 * s;
;                     u32x4 w; w.x = cvt_pk_bf16(o0[0], o0[1]); w.y = cvt_pk_bf16(o0[2], o0[3]); w.z = cvt_pk_bf16(o1[0], o1[1]); w.w = cvt_pk_bf16(o1[2], o1[3]);
;                     *(u32x4*)(rowp + bj * 32) = w; }
	v_add_f32_e32 v146, v146, v209
	ds_bpermute_b32 v209, v207, v146
	s_waitcnt lgkmcnt(0)
	v_add_f32_e32 v146, v146, v209
	v_fmamk_f32 v146, v146, 0x3c800000, v200
	v_rsq_f32_e32 v146, v146
	v_mul_f32_e32 v209, v10, v10
	v_pk_mul_f32 v[220:221], v[46:47], v[146:147] op_sel_hi:[1,0]
	v_pk_mul_f32 v[222:223], v[48:49], v[146:147] op_sel_hi:[1,0]
	v_pk_mul_f32 v[214:215], v[56:57], v[146:147] op_sel_hi:[1,0]
	v_pk_mul_f32 v[216:217], v[54:55], v[146:147] op_sel_hi:[1,0]
	v_pk_mul_f32 v[222:223], v[182:183], v[222:223]
	v_pk_mul_f32 v[220:221], v[184:185], v[220:221]
	v_pk_mul_f32 v[228:229], v[26:27], v[146:147] op_sel_hi:[1,0]
	v_pk_mul_f32 v[230:231], v[28:29], v[146:147] op_sel_hi:[1,0]
	v_pk_mul_f32 v[216:217], v[190:191], v[216:217]
	v_pk_mul_f32 v[214:215], v[178:179], v[214:215]
	v_pk_mul_f32 v[232:233], v[130:131], v[220:221]
	v_pk_mul_f32 v[234:235], v[132:133], v[222:223]
	v_pk_mul_f32 v[220:221], v[134:135], v[220:221]
	v_pk_mul_f32 v[222:223], v[136:137], v[222:223]
	v_pk_mul_f32 v[224:225], v[36:37], v[146:147] op_sel_hi:[1,0]
	v_pk_mul_f32 v[226:227], v[34:35], v[146:147] op_sel_hi:[1,0]
	v_pk_mul_f32 v[230:231], v[186:187], v[230:231]
	v_pk_mul_f32 v[228:229], v[188:189], v[228:229]
	v_pk_fma_f32 v[234:235], v[136:137], v[214:215], v[234:235] neg_lo:[0,0,1] neg_hi:[0,0,1]
	v_pk_fma_f32 v[232:233], v[134:135], v[216:217], v[232:233] neg_lo:[0,0,1] neg_hi:[0,0,1]
	v_pk_fma_f32 v[222:223], v[132:133], v[214:215], v[222:223]
	v_pk_fma_f32 v[216:217], v[130:131], v[216:217], v[220:221]
	v_cvt_pk_bf16_f32 v214, v232, v233
	v_cvt_pk_bf16_f32 v215, v234, v235
	v_pk_mul_f32 v[226:227], v[192:193], v[226:227]
	v_pk_mul_f32 v[224:225], v[180:181], v[224:225]
	v_cvt_pk_bf16_f32 v216, v216, v217
	v_cvt_pk_bf16_f32 v217, v222, v223
	global_store_dwordx4 v[218:219], v[214:217], off
	v_mul_f32_e32 v146, v19, v19
	s_waitcnt lgkmcnt(0)
	v_pk_mul_f32 v[220:221], v[210:211], v[228:229]
	v_pk_mul_f32 v[214:215], v[194:195], v[228:229]
	v_pk_mul_f32 v[222:223], v[212:213], v[230:231]
	v_pk_mul_f32 v[216:217], v[196:197], v[230:231]
	v_pk_fma_f32 v[210:211], v[210:211], v[226:227], v[214:215] neg_lo:[0,0,1] neg_hi:[0,0,1]
	v_pk_fma_f32 v[214:215], v[196:197], v[224:225], v[222:223]
	v_pk_fma_f32 v[196:197], v[194:195], v[226:227], v[220:221]
	v_pk_fma_f32 v[212:213], v[212:213], v[224:225], v[216:217] neg_lo:[0,0,1] neg_hi:[0,0,1]
	v_cvt_pk_bf16_f32 v194, v210, v211
	v_pk_mul_f32 v[216:217], v[38:39], v[38:39]
	v_cvt_pk_bf16_f32 v195, v212, v213
	v_cvt_pk_bf16_f32 v196, v196, v197
	v_cvt_pk_bf16_f32 v197, v214, v215
	global_store_dwordx4 v[218:219], v[194:197], off offset:64
	v_subrev_u32_e32 v252, s98, v164
	v_bfe_u32 v253, v252, 13, 1
	v_and_b32_e32 v252, 0xfff, v252
	v_lshl_or_b32 v252, v253, 12, v252
	v_add_u32_e32 v252, 0x20800, v252
	ds_read_b128 v[194:197], v252
	s_nop 0
	v_subrev_u32_e32 v252, s98, v162
	v_bfe_u32 v253, v252, 13, 1
	v_and_b32_e32 v252, 0xfff, v252
	v_lshl_or_b32 v252, v253, 12, v252
	v_add_u32_e32 v252, 0x20800, v252
	ds_read_b128 v[210:213], v252
	v_pk_mul_f32 v[214:215], v[40:41], v[40:41]
	v_pk_mul_f32 v[220:221], v[32:33], v[32:33]
	v_pk_mul_f32 v[222:223], v[30:31], v[30:31]
	v_pk_mov_b32 v[226:227], v[216:217], v[214:215] op_sel:[1,0]
	v_mov_b32_e32 v217, v215
	v_pk_mov_b32 v[214:215], v[222:223], v[220:221] op_sel:[1,0]
	v_mov_b32_e32 v223, v221
	v_mul_f32_e32 v224, v21, v21
	v_pk_add_f32 v[216:217], v[226:227], v[216:217]
	v_pk_add_f32 v[214:215], v[214:215], v[222:223]
	v_mul_f32_e32 v228, v11, v11
	v_mul_f32_e32 v229, v12, v12
	v_mul_f32_e32 v230, v13, v13
	v_pk_fma_f32 v[220:221], v[18:19], v[18:19], v[146:147] op_sel_hi:[1,1,0]
	v_pk_fma_f32 v[224:225], v[20:21], v[20:21], v[224:225] op_sel_hi:[1,1,0]
	v_pk_add_f32 v[216:217], v[216:217], v[216:217] op_sel:[0,1] op_sel_hi:[1,0]
	v_pk_add_f32 v[214:215], v[214:215], v[214:215] op_sel:[0,1] op_sel_hi:[1,0]
	v_mov_b32_e32 v221, v229
	v_mov_b32_e32 v225, v230
	v_mov_b32_e32 v217, v209
	v_mov_b32_e32 v215, v228
	v_pk_add_f32 v[220:221], v[220:221], v[224:225]
	v_pk_add_f32 v[214:215], v[216:217], v[214:215]
	v_lshl_add_u64 v[218:219], v[218:219], 0, s[12:13]
	v_pk_add_f32 v[214:215], v[214:215], v[220:221]
	s_nop 0
	v_add_f32_e32 v146, v214, v215
	ds_bpermute_b32 v209, v177, v146
	s_waitcnt lgkmcnt(0)
	v_add_f32_e32 v146, v146, v209
	ds_bpermute_b32 v209, v207, v146
	s_waitcnt lgkmcnt(0)
	v_add_f32_e32 v146, v146, v209
	v_fmamk_f32 v146, v146, 0x3c800000, v200
	v_rsq_f32_e32 v146, v146
	v_mul_f32_e32 v209, v2, v2
	v_pk_mul_f32 v[220:221], v[30:31], v[146:147] op_sel_hi:[1,0]
	v_pk_mul_f32 v[222:223], v[32:33], v[146:147] op_sel_hi:[1,0]
	v_pk_mul_f32 v[214:215], v[40:41], v[146:147] op_sel_hi:[1,0]
	v_pk_mul_f32 v[216:217], v[38:39], v[146:147] op_sel_hi:[1,0]
	v_pk_mul_f32 v[222:223], v[182:183], v[222:223]
	v_pk_mul_f32 v[220:221], v[184:185], v[220:221]
	v_pk_mul_f32 v[228:229], v[10:11], v[146:147] op_sel_hi:[1,0]
	v_pk_mul_f32 v[230:231], v[12:13], v[146:147] op_sel_hi:[1,0]
	v_pk_mul_f32 v[216:217], v[190:191], v[216:217]
	v_pk_mul_f32 v[214:215], v[178:179], v[214:215]
	v_pk_mul_f32 v[232:233], v[130:131], v[220:221]
	v_pk_mul_f32 v[234:235], v[132:133], v[222:223]
	v_pk_mul_f32 v[220:221], v[134:135], v[220:221]
	v_pk_mul_f32 v[222:223], v[136:137], v[222:223]
	v_pk_mul_f32 v[224:225], v[20:21], v[146:147] op_sel_hi:[1,0]
	v_pk_mul_f32 v[226:227], v[18:19], v[146:147] op_sel_hi:[1,0]
	v_pk_mul_f32 v[230:231], v[186:187], v[230:231]
	v_pk_mul_f32 v[228:229], v[188:189], v[228:229]
	v_pk_fma_f32 v[234:235], v[136:137], v[214:215], v[234:235] neg_lo:[0,0,1] neg_hi:[0,0,1]
	v_pk_fma_f32 v[232:233], v[134:135], v[216:217], v[232:233] neg_lo:[0,0,1] neg_hi:[0,0,1]
	v_pk_fma_f32 v[222:223], v[132:133], v[214:215], v[222:223]
	v_pk_fma_f32 v[216:217], v[130:131], v[216:217], v[220:221]
	v_cvt_pk_bf16_f32 v214, v232, v233
	v_cvt_pk_bf16_f32 v215, v234, v235
	v_pk_mul_f32 v[226:227], v[192:193], v[226:227]
	v_pk_mul_f32 v[224:225], v[180:181], v[224:225]
	v_cvt_pk_bf16_f32 v216, v216, v217
	v_cvt_pk_bf16_f32 v217, v222, v223
	global_store_dwordx4 v[218:219], v[214:217], off
	v_mul_f32_e32 v146, v7, v7
	s_waitcnt lgkmcnt(0)
; __device__ __forceinline__ unsigned cvt_pk_bf16(float lo, float hi) { unsigned r; asm volatile("v_cvt_pk_bf16_f32 %0, %1, %2" : "=v"(r) : "v"(lo), "v"(hi)); return r; }
;     __device__ __forceinline__ void operator()(const f32x4 (&acc)[2][2][4][2], const Unit& u, int wr, int wc, int fr, int fq) const {
;     ...
;             for (int m = 0; m < 4; ++m) {
;                 const int pcol = 16 * m + fr;
;                 const f32x4 cc = *(const f32x4*)(cosT + pcol * 16 + 4 * fq), sn = *(const f32x4*)(sinT + pcol * 16 + 4 * fq);
;                 float ss = 0.f;
; #pragma unroll
;                 for (int bj = 0; bj < 2; ++bj)
; #pragma unroll
;                     for (int n = 0; n < 2; ++n) { const f32x4 x = acc[ai][bj][m][n]; ss += (x[0] * x[0] + x[1] * x[1]) + (x[2] * x[2] + x[3] * x[3]); }
;                 ss += __shfl_xor(ss, 16); ss += __shfl_xor(ss, 32);
;                 const float rstd = __builtin_amdgcn_rsqf(ss * (1.0f / 64.0f) + RMS_EPS);
;                 bf16_t* rowp = base + (size_t)(ai * HALF + m * 16) * pitch;
; #pragma unroll
;                 for (int bj = 0; bj < 2; ++bj) { const f32x4 c = bj == 0 ? cr : cc, s = bj == 0 ? sr : sn;
;                     const f32x4 y0 = acc[ai][bj][m][0] * rstd * gv[bj][0], y1 = acc[ai][bj][m][1] * rstd * gv[bj][1];
;                     const f32x4 o0 = y0 * c - y1 * s, o1 = y1 * c + y0 * s;
;                     u32x4 w; w.x = cvt_pk_bf16(o0[0], o0[1]); w.y = cvt_pk_bf16(o0[2], o0[3]); w.z = cvt_pk_bf16(o1[0], o1[1]); w.w = cvt_pk_bf16(o1[2], o1[3]);
;                     *(u32x4*)(rowp + bj * 32) = w; }
	v_pk_mul_f32 v[220:221], v[210:211], v[228:229]
	v_pk_mul_f32 v[214:215], v[194:195], v[228:229]
	v_pk_mul_f32 v[222:223], v[212:213], v[230:231]
	v_pk_mul_f32 v[216:217], v[196:197], v[230:231]
	v_pk_fma_f32 v[210:211], v[210:211], v[226:227], v[214:215] neg_lo:[0,0,1] neg_hi:[0,0,1]
	v_pk_fma_f32 v[214:215], v[196:197], v[224:225], v[222:223]
	v_pk_fma_f32 v[196:197], v[194:195], v[226:227], v[220:221]
	v_pk_fma_f32 v[212:213], v[212:213], v[224:225], v[216:217] neg_lo:[0,0,1] neg_hi:[0,0,1]
	v_cvt_pk_bf16_f32 v194, v210, v211
	v_pk_mul_f32 v[216:217], v[22:23], v[22:23]
	v_cvt_pk_bf16_f32 v195, v212, v213
	v_cvt_pk_bf16_f32 v196, v196, v197
	v_cvt_pk_bf16_f32 v197, v214, v215
	global_store_dwordx4 v[218:219], v[194:197], off offset:64
	v_subrev_u32_e32 v252, s98, v168
	v_bfe_u32 v253, v252, 13, 1
	v_and_b32_e32 v252, 0xfff, v252
	v_lshl_or_b32 v252, v253, 12, v252
	v_add_u32_e32 v252, 0x20800, v252
	ds_read_b128 v[194:197], v252
	s_nop 0
	v_subrev_u32_e32 v252, s98, v166
	v_bfe_u32 v253, v252, 13, 1
	v_and_b32_e32 v252, 0xfff, v252
	v_lshl_or_b32 v252, v253, 12, v252
	v_add_u32_e32 v252, 0x20800, v252
	ds_read_b128 v[210:213], v252
	v_pk_mul_f32 v[214:215], v[24:25], v[24:25]
	v_pk_mul_f32 v[220:221], v[16:17], v[16:17]
	v_pk_mul_f32 v[222:223], v[14:15], v[14:15]
	v_pk_mov_b32 v[226:227], v[216:217], v[214:215] op_sel:[1,0]
	v_mov_b32_e32 v217, v215
	v_pk_mov_b32 v[214:215], v[222:223], v[220:221] op_sel:[1,0]
	v_mov_b32_e32 v223, v221
	v_mul_f32_e32 v224, v9, v9
	v_pk_add_f32 v[216:217], v[226:227], v[216:217]
	v_pk_add_f32 v[214:215], v[214:215], v[222:223]
	v_mul_f32_e32 v228, v3, v3
	v_mul_f32_e32 v229, v4, v4
	v_mul_f32_e32 v230, v5, v5
	v_pk_fma_f32 v[220:221], v[6:7], v[6:7], v[146:147] op_sel_hi:[1,1,0]
	v_pk_fma_f32 v[224:225], v[8:9], v[8:9], v[224:225] op_sel_hi:[1,1,0]
	v_pk_add_f32 v[216:217], v[216:217], v[216:217] op_sel:[0,1] op_sel_hi:[1,0]
	v_pk_add_f32 v[214:215], v[214:215], v[214:215] op_sel:[0,1] op_sel_hi:[1,0]
	v_mov_b32_e32 v221, v229
	v_mov_b32_e32 v225, v230
	v_mov_b32_e32 v217, v209
	v_mov_b32_e32 v215, v228
	v_pk_add_f32 v[220:221], v[220:221], v[224:225]
	v_pk_add_f32 v[214:215], v[216:217], v[214:215]
	s_nop 0
	v_pk_add_f32 v[214:215], v[214:215], v[220:221]
	s_nop 0
	v_add_f32_e32 v146, v214, v215
	ds_bpermute_b32 v177, v177, v146
	v_lshl_add_u64 v[214:215], v[218:219], 0, s[12:13]
	s_waitcnt lgkmcnt(0)
	v_add_f32_e32 v146, v146, v177
	ds_bpermute_b32 v177, v207, v146
	s_waitcnt lgkmcnt(0)
	v_add_f32_e32 v146, v146, v177
	v_fmamk_f32 v146, v146, 0x3c800000, v200
	v_rsq_f32_e32 v146, v146
	s_nop 0
	v_pk_mul_f32 v[220:221], v[14:15], v[146:147] op_sel_hi:[1,0]
	v_pk_mul_f32 v[222:223], v[16:17], v[146:147] op_sel_hi:[1,0]
	v_pk_mul_f32 v[216:217], v[24:25], v[146:147] op_sel_hi:[1,0]
	v_pk_mul_f32 v[218:219], v[22:23], v[146:147] op_sel_hi:[1,0]
	v_pk_mul_f32 v[182:183], v[182:183], v[222:223]
	v_pk_mul_f32 v[184:185], v[184:185], v[220:221]
	v_pk_mul_f32 v[190:191], v[190:191], v[218:219]
	v_pk_mul_f32 v[178:179], v[178:179], v[216:217]
	v_pk_mul_f32 v[216:217], v[130:131], v[184:185]
	v_pk_mul_f32 v[218:219], v[132:133], v[182:183]
	v_pk_mul_f32 v[184:185], v[134:135], v[184:185]
	v_pk_mul_f32 v[182:183], v[136:137], v[182:183]
	v_pk_mul_f32 v[228:229], v[2:3], v[146:147] op_sel_hi:[1,0]
	v_pk_mul_f32 v[230:231], v[4:5], v[146:147] op_sel_hi:[1,0]
	v_pk_fma_f32 v[136:137], v[136:137], v[178:179], v[218:219] neg_lo:[0,0,1] neg_hi:[0,0,1]
	v_pk_fma_f32 v[178:179], v[132:133], v[178:179], v[182:183]
	v_pk_fma_f32 v[132:133], v[130:131], v[190:191], v[184:185]
	v_pk_mul_f32 v[224:225], v[8:9], v[146:147] op_sel_hi:[1,0]
	v_pk_mul_f32 v[226:227], v[6:7], v[146:147] op_sel_hi:[1,0]
	v_pk_mul_f32 v[186:187], v[186:187], v[230:231]
	v_pk_mul_f32 v[188:189], v[188:189], v[228:229]
	v_pk_fma_f32 v[134:135], v[134:135], v[190:191], v[216:217] neg_lo:[0,0,1] neg_hi:[0,0,1]
	v_pk_mul_f32 v[192:193], v[192:193], v[226:227]
	v_cvt_pk_bf16_f32 v130, v134, v135
	v_cvt_pk_bf16_f32 v131, v136, v137
	v_cvt_pk_bf16_f32 v132, v132, v133
	v_cvt_pk_bf16_f32 v133, v178, v179
	v_pk_mul_f32 v[180:181], v[180:181], v[224:225]
	global_store_dwordx4 v[214:215], v[130:133], off
	s_waitcnt lgkmcnt(0)
	v_pk_mul_f32 v[134:135], v[210:211], v[188:189]
	v_pk_mul_f32 v[130:131], v[194:195], v[188:189]
	v_pk_mul_f32 v[132:133], v[196:197], v[186:187]
	v_pk_mul_f32 v[136:137], v[212:213], v[186:187]
	v_pk_fma_f32 v[132:133], v[212:213], v[180:181], v[132:133] neg_lo:[0,0,1] neg_hi:[0,0,1]
	v_pk_fma_f32 v[130:131], v[210:211], v[192:193], v[130:131] neg_lo:[0,0,1] neg_hi:[0,0,1]
	v_pk_fma_f32 v[136:137], v[196:197], v[180:181], v[136:137]
	v_pk_fma_f32 v[134:135], v[194:195], v[192:193], v[134:135]
	v_cvt_pk_bf16_f32 v130, v130, v131
	v_cvt_pk_bf16_f32 v131, v132, v133
	s_nop 0
	v_cvt_pk_bf16_f32 v132, v134, v135
	v_cvt_pk_bf16_f32 v133, v136, v137
	global_store_dwordx4 v[214:215], v[130:133], off offset:64
